# P4W: out-proj pair GEMM half-steps also start their first four MFMAs on counted lgkmcnt before the LDS-release barrier (on v137)
# speedup vs baseline: 1.0008x; 1.0008x over previous
.Lg1o_loop:
	ds_read_b128 v[76:79], v68 offset:0
	ds_read_b128 v[80:83], v68 offset:4096
	ds_read_b128 v[148:151], v69 offset:0
	ds_read_b128 v[152:155], v69 offset:4096
	ds_read_b128 v[84:87], v70 offset:0
	ds_read_b128 v[88:91], v70 offset:4096
	ds_read_b128 v[180:183], v71 offset:0
	ds_read_b128 v[236:239], v71 offset:4096
	ds_read_b128 v[92:95], v72 offset:0
	ds_read_b128 v[96:99], v72 offset:4096
	ds_read_b128 v[240:243], v73 offset:0
	ds_read_b128 v[244:247], v73 offset:4096
	ds_read_b128 v[100:103], v74 offset:0
	ds_read_b128 v[144:147], v74 offset:4096
	ds_read_b128 v[248:251], v75 offset:0
	ds_read_b128 v[252:255], v75 offset:4096
	s_waitcnt lgkmcnt(12)
	v_mfma_f32_32x32x16_bf16 v[50:65], v[76:79], v[148:151], v[50:65]
	v_mfma_f32_32x32x16_bf16 v[34:49], v[76:79], v[152:155], v[34:49]
	v_mfma_f32_32x32x16_bf16 v[18:33], v[80:83], v[148:151], v[18:33]
	v_mfma_f32_32x32x16_bf16 v[2:17], v[80:83], v[152:155], v[2:17]
	s_waitcnt lgkmcnt(0)
	s_barrier
	s_mov_b32 m0, s5
	v_mfma_f32_32x32x16_bf16 v[50:65], v[84:87], v[180:183], v[50:65]
	global_load_lds_dwordx4 v[104:105], off
	v_mfma_f32_32x32x16_bf16 v[34:49], v[84:87], v[236:239], v[34:49]
	s_add_i32 m0, s5, 0x400
	v_mfma_f32_32x32x16_bf16 v[18:33], v[88:91], v[180:183], v[18:33]
	global_load_lds_dwordx4 v[108:109], off
	v_mfma_f32_32x32x16_bf16 v[2:17], v[88:91], v[236:239], v[2:17]
	s_add_i32 m0, s5, 0x800
	v_mfma_f32_32x32x16_bf16 v[50:65], v[92:95], v[240:243], v[50:65]
	global_load_lds_dwordx4 v[112:113], off
	v_mfma_f32_32x32x16_bf16 v[34:49], v[92:95], v[244:247], v[34:49]
	s_add_i32 m0, s5, 0xc00
	v_mfma_f32_32x32x16_bf16 v[18:33], v[96:99], v[240:243], v[18:33]
	global_load_lds_dwordx4 v[116:117], off
	v_mfma_f32_32x32x16_bf16 v[2:17], v[96:99], v[244:247], v[2:17]
	s_mov_b32 m0, s15
	v_mfma_f32_32x32x16_bf16 v[50:65], v[100:103], v[248:251], v[50:65]
	global_load_lds_dwordx4 v[106:107], off
	v_lshl_add_u64 v[106:107], v[106:107], 0, s[34:35]
	v_mfma_f32_32x32x16_bf16 v[34:49], v[100:103], v[252:255], v[34:49]
	s_mov_b32 m0, s16
	v_mfma_f32_32x32x16_bf16 v[18:33], v[144:147], v[248:251], v[18:33]
	global_load_lds_dwordx4 v[110:111], off
	v_lshl_add_u64 v[110:111], v[110:111], 0, s[34:35]
	v_mfma_f32_32x32x16_bf16 v[2:17], v[144:147], v[252:255], v[2:17]
	s_waitcnt vmcnt(8)
	s_barrier
	ds_read_b128 v[76:79], v68 offset:32768
	ds_read_b128 v[80:83], v68 offset:36864
	ds_read_b128 v[84:87], v70 offset:32768
	ds_read_b128 v[88:91], v70 offset:36864
	ds_read_b128 v[92:95], v72 offset:32768
	ds_read_b128 v[96:99], v72 offset:36864
	ds_read_b128 v[100:103], v74 offset:32768
	ds_read_b128 v[144:147], v74 offset:36864
	s_waitcnt lgkmcnt(6)
	v_mfma_f32_32x32x16_bf16 v[128:143], v[76:79], v[148:151], v[128:143]
	v_mfma_f32_32x32x16_bf16 v[184:199], v[76:79], v[152:155], v[184:199]
	v_mfma_f32_32x32x16_bf16 v[200:215], v[80:83], v[148:151], v[200:215]
	v_mfma_f32_32x32x16_bf16 v[216:231], v[80:83], v[152:155], v[216:231]
	s_waitcnt lgkmcnt(0)
	s_barrier
	s_add_i32 m0, s5, 0x8000
	v_lshl_add_u64 v[66:67], v[104:105], 0, s[8:9]
	v_mfma_f32_32x32x16_bf16 v[128:143], v[84:87], v[180:183], v[128:143]
	global_load_lds_dwordx4 v[66:67], off
	v_lshl_add_u64 v[104:105], v[104:105], 0, s[34:35]
	v_mfma_f32_32x32x16_bf16 v[184:199], v[84:87], v[236:239], v[184:199]
	s_add_i32 m0, s5, 0x8400
	v_lshl_add_u64 v[66:67], v[108:109], 0, s[8:9]
	v_mfma_f32_32x32x16_bf16 v[200:215], v[88:91], v[180:183], v[200:215]
	global_load_lds_dwordx4 v[66:67], off
	v_lshl_add_u64 v[108:109], v[108:109], 0, s[34:35]
	v_mfma_f32_32x32x16_bf16 v[216:231], v[88:91], v[236:239], v[216:231]
	s_add_i32 m0, s5, 0x8800
	v_lshl_add_u64 v[66:67], v[112:113], 0, s[8:9]
	v_mfma_f32_32x32x16_bf16 v[128:143], v[92:95], v[240:243], v[128:143]
	global_load_lds_dwordx4 v[66:67], off
	v_lshl_add_u64 v[112:113], v[112:113], 0, s[34:35]
	v_mfma_f32_32x32x16_bf16 v[184:199], v[92:95], v[244:247], v[184:199]
	s_add_i32 m0, s5, 0x8c00
	v_lshl_add_u64 v[66:67], v[116:117], 0, s[8:9]
	v_mfma_f32_32x32x16_bf16 v[200:215], v[96:99], v[240:243], v[200:215]
	global_load_lds_dwordx4 v[66:67], off
	v_lshl_add_u64 v[116:117], v[116:117], 0, s[34:35]
	v_mfma_f32_32x32x16_bf16 v[216:231], v[96:99], v[244:247], v[216:231]
	s_mov_b32 m0, s17
	v_mfma_f32_32x32x16_bf16 v[128:143], v[100:103], v[248:251], v[128:143]
	global_load_lds_dwordx4 v[114:115], off
	v_lshl_add_u64 v[114:115], v[114:115], 0, s[34:35]
	v_mfma_f32_32x32x16_bf16 v[184:199], v[100:103], v[252:255], v[184:199]
	s_mov_b32 m0, s22
	v_mfma_f32_32x32x16_bf16 v[200:215], v[144:147], v[248:251], v[200:215]
	global_load_lds_dwordx4 v[118:119], off
	v_lshl_add_u64 v[118:119], v[118:119], 0, s[34:35]
	v_mfma_f32_32x32x16_bf16 v[216:231], v[144:147], v[252:255], v[216:231]
	s_waitcnt vmcnt(8)
	s_barrier
	ds_read_b128 v[76:79], v68 offset:0
	ds_read_b128 v[80:83], v68 offset:4096
	ds_read_b128 v[148:151], v69 offset:32768
	ds_read_b128 v[152:155], v69 offset:36864
	ds_read_b128 v[84:87], v70 offset:0
	ds_read_b128 v[88:91], v70 offset:4096
	ds_read_b128 v[180:183], v71 offset:32768
	ds_read_b128 v[236:239], v71 offset:36864
	ds_read_b128 v[92:95], v72 offset:0
	ds_read_b128 v[96:99], v72 offset:4096
	ds_read_b128 v[240:243], v73 offset:32768
	ds_read_b128 v[244:247], v73 offset:36864
	ds_read_b128 v[100:103], v74 offset:0
	ds_read_b128 v[144:147], v74 offset:4096
	ds_read_b128 v[248:251], v75 offset:32768
	ds_read_b128 v[252:255], v75 offset:36864
	s_waitcnt lgkmcnt(12)
	v_mfma_f32_32x32x16_bf16 v[50:65], v[76:79], v[148:151], v[50:65]
	v_mfma_f32_32x32x16_bf16 v[34:49], v[76:79], v[152:155], v[34:49]
	v_mfma_f32_32x32x16_bf16 v[18:33], v[80:83], v[148:151], v[18:33]
	v_mfma_f32_32x32x16_bf16 v[2:17], v[80:83], v[152:155], v[2:17]
	s_waitcnt lgkmcnt(0)
	s_barrier
	s_mov_b32 m0, s5
	v_mfma_f32_32x32x16_bf16 v[50:65], v[84:87], v[180:183], v[50:65]
	global_load_lds_dwordx4 v[104:105], off
	v_mfma_f32_32x32x16_bf16 v[34:49], v[84:87], v[236:239], v[34:49]
	s_add_i32 m0, s5, 0x400
	v_mfma_f32_32x32x16_bf16 v[18:33], v[88:91], v[180:183], v[18:33]
	global_load_lds_dwordx4 v[108:109], off
	v_mfma_f32_32x32x16_bf16 v[2:17], v[88:91], v[236:239], v[2:17]
	s_add_i32 m0, s5, 0x800
	v_mfma_f32_32x32x16_bf16 v[50:65], v[92:95], v[240:243], v[50:65]
	global_load_lds_dwordx4 v[112:113], off
	v_mfma_f32_32x32x16_bf16 v[34:49], v[92:95], v[244:247], v[34:49]
	s_add_i32 m0, s5, 0xc00
	v_mfma_f32_32x32x16_bf16 v[18:33], v[96:99], v[240:243], v[18:33]
	global_load_lds_dwordx4 v[116:117], off
	v_mfma_f32_32x32x16_bf16 v[2:17], v[96:99], v[244:247], v[2:17]
	s_add_i32 m0, s5, 0xc000
	v_mfma_f32_32x32x16_bf16 v[50:65], v[100:103], v[248:251], v[50:65]
	global_load_lds_dwordx4 v[106:107], off
	v_lshl_add_u64 v[106:107], v[106:107], 0, s[34:35]
	v_mfma_f32_32x32x16_bf16 v[34:49], v[100:103], v[252:255], v[34:49]
	s_add_i32 m0, s5, 0xc400
	v_mfma_f32_32x32x16_bf16 v[18:33], v[144:147], v[248:251], v[18:33]
	global_load_lds_dwordx4 v[110:111], off
	v_lshl_add_u64 v[110:111], v[110:111], 0, s[34:35]
	v_mfma_f32_32x32x16_bf16 v[2:17], v[144:147], v[252:255], v[2:17]
	s_waitcnt vmcnt(8)
	s_barrier
	ds_read_b128 v[76:79], v68 offset:32768
	ds_read_b128 v[80:83], v68 offset:36864
	ds_read_b128 v[84:87], v70 offset:32768
	ds_read_b128 v[88:91], v70 offset:36864
	ds_read_b128 v[92:95], v72 offset:32768
	ds_read_b128 v[96:99], v72 offset:36864
	ds_read_b128 v[100:103], v74 offset:32768
	ds_read_b128 v[144:147], v74 offset:36864
	s_waitcnt lgkmcnt(6)
	v_mfma_f32_32x32x16_bf16 v[128:143], v[76:79], v[148:151], v[128:143]
	v_mfma_f32_32x32x16_bf16 v[184:199], v[76:79], v[152:155], v[184:199]
	v_mfma_f32_32x32x16_bf16 v[200:215], v[80:83], v[148:151], v[200:215]
	v_mfma_f32_32x32x16_bf16 v[216:231], v[80:83], v[152:155], v[216:231]
	s_waitcnt lgkmcnt(0)
	s_barrier
	s_add_i32 m0, s5, 0x8000
	v_lshl_add_u64 v[66:67], v[104:105], 0, s[8:9]
	v_mfma_f32_32x32x16_bf16 v[128:143], v[84:87], v[180:183], v[128:143]
	global_load_lds_dwordx4 v[66:67], off
	v_lshl_add_u64 v[104:105], v[104:105], 0, s[34:35]
	v_mfma_f32_32x32x16_bf16 v[184:199], v[84:87], v[236:239], v[184:199]
	s_add_i32 m0, s5, 0x8400
	v_lshl_add_u64 v[66:67], v[108:109], 0, s[8:9]
	v_mfma_f32_32x32x16_bf16 v[200:215], v[88:91], v[180:183], v[200:215]
	global_load_lds_dwordx4 v[66:67], off
	v_lshl_add_u64 v[108:109], v[108:109], 0, s[34:35]
	v_mfma_f32_32x32x16_bf16 v[216:231], v[88:91], v[236:239], v[216:231]
	s_add_i32 m0, s5, 0x8800
	v_lshl_add_u64 v[66:67], v[112:113], 0, s[8:9]
	v_mfma_f32_32x32x16_bf16 v[128:143], v[92:95], v[240:243], v[128:143]
	global_load_lds_dwordx4 v[66:67], off
	v_lshl_add_u64 v[112:113], v[112:113], 0, s[34:35]
	v_mfma_f32_32x32x16_bf16 v[184:199], v[92:95], v[244:247], v[184:199]
	s_add_i32 m0, s5, 0x8c00
	v_lshl_add_u64 v[66:67], v[116:117], 0, s[8:9]
	v_mfma_f32_32x32x16_bf16 v[200:215], v[96:99], v[240:243], v[200:215]
	global_load_lds_dwordx4 v[66:67], off
	v_lshl_add_u64 v[116:117], v[116:117], 0, s[34:35]
	v_mfma_f32_32x32x16_bf16 v[216:231], v[96:99], v[244:247], v[216:231]
	s_add_i32 m0, s5, 0xc800
	v_mfma_f32_32x32x16_bf16 v[128:143], v[100:103], v[248:251], v[128:143]
	global_load_lds_dwordx4 v[114:115], off
	v_lshl_add_u64 v[114:115], v[114:115], 0, s[34:35]
	v_mfma_f32_32x32x16_bf16 v[184:199], v[100:103], v[252:255], v[184:199]
	s_add_i32 m0, s5, 0xcc00
	v_mfma_f32_32x32x16_bf16 v[200:215], v[144:147], v[248:251], v[200:215]
	global_load_lds_dwordx4 v[118:119], off
	v_lshl_add_u64 v[118:119], v[118:119], 0, s[34:35]
	v_mfma_f32_32x32x16_bf16 v[216:231], v[144:147], v[252:255], v[216:231]
	s_waitcnt vmcnt(8)
	s_barrier
	s_add_i32 s23, s23, 2
	s_cmp_lt_u32 s23, 14
	s_cbranch_scc1 .Lg1o_loop
	ds_read_b128 v[76:79], v68 offset:0
	ds_read_b128 v[80:83], v68 offset:4096
	ds_read_b128 v[148:151], v69 offset:0
	ds_read_b128 v[152:155], v69 offset:4096
	ds_read_b128 v[84:87], v70 offset:0
	ds_read_b128 v[88:91], v70 offset:4096
	ds_read_b128 v[180:183], v71 offset:0
	ds_read_b128 v[236:239], v71 offset:4096
	ds_read_b128 v[92:95], v72 offset:0
	ds_read_b128 v[96:99], v72 offset:4096
	ds_read_b128 v[240:243], v73 offset:0
	ds_read_b128 v[244:247], v73 offset:4096
	ds_read_b128 v[100:103], v74 offset:0
	ds_read_b128 v[144:147], v74 offset:4096
	ds_read_b128 v[248:251], v75 offset:0
	ds_read_b128 v[252:255], v75 offset:4096
	s_waitcnt lgkmcnt(12)
	v_mfma_f32_32x32x16_bf16 v[50:65], v[76:79], v[148:151], v[50:65]
	v_mfma_f32_32x32x16_bf16 v[34:49], v[76:79], v[152:155], v[34:49]
	v_mfma_f32_32x32x16_bf16 v[18:33], v[80:83], v[148:151], v[18:33]
	v_mfma_f32_32x32x16_bf16 v[2:17], v[80:83], v[152:155], v[2:17]
	s_waitcnt lgkmcnt(0)
	s_barrier
	s_mov_b32 m0, s5
	v_mfma_f32_32x32x16_bf16 v[50:65], v[84:87], v[180:183], v[50:65]
	global_load_lds_dwordx4 v[104:105], off
	v_mfma_f32_32x32x16_bf16 v[34:49], v[84:87], v[236:239], v[34:49]
	s_add_i32 m0, s5, 0x400
	v_mfma_f32_32x32x16_bf16 v[18:33], v[88:91], v[180:183], v[18:33]
	global_load_lds_dwordx4 v[108:109], off
	v_mfma_f32_32x32x16_bf16 v[2:17], v[88:91], v[236:239], v[2:17]
	s_add_i32 m0, s5, 0x800
	v_mfma_f32_32x32x16_bf16 v[50:65], v[92:95], v[240:243], v[50:65]
	global_load_lds_dwordx4 v[112:113], off
	v_mfma_f32_32x32x16_bf16 v[34:49], v[92:95], v[244:247], v[34:49]
	s_add_i32 m0, s5, 0xc00
	v_mfma_f32_32x32x16_bf16 v[18:33], v[96:99], v[240:243], v[18:33]
	global_load_lds_dwordx4 v[116:117], off
	v_mfma_f32_32x32x16_bf16 v[2:17], v[96:99], v[244:247], v[2:17]
	v_mfma_f32_32x32x16_bf16 v[50:65], v[100:103], v[248:251], v[50:65]
	v_mfma_f32_32x32x16_bf16 v[34:49], v[100:103], v[252:255], v[34:49]
	v_mfma_f32_32x32x16_bf16 v[18:33], v[144:147], v[248:251], v[18:33]
	v_mfma_f32_32x32x16_bf16 v[2:17], v[144:147], v[252:255], v[2:17]
	s_waitcnt vmcnt(4)
	s_barrier
	ds_read_b128 v[76:79], v68 offset:32768
	ds_read_b128 v[80:83], v68 offset:36864
	ds_read_b128 v[84:87], v70 offset:32768
	ds_read_b128 v[88:91], v70 offset:36864
	ds_read_b128 v[92:95], v72 offset:32768
	ds_read_b128 v[96:99], v72 offset:36864
	ds_read_b128 v[100:103], v74 offset:32768
	ds_read_b128 v[144:147], v74 offset:36864
	s_waitcnt lgkmcnt(6)
	v_mfma_f32_32x32x16_bf16 v[128:143], v[76:79], v[148:151], v[128:143]
	v_mfma_f32_32x32x16_bf16 v[184:199], v[76:79], v[152:155], v[184:199]
	v_mfma_f32_32x32x16_bf16 v[200:215], v[80:83], v[148:151], v[200:215]
	v_mfma_f32_32x32x16_bf16 v[216:231], v[80:83], v[152:155], v[216:231]
	s_waitcnt lgkmcnt(0)
	s_barrier
	s_add_i32 m0, s5, 0x8000
	v_lshl_add_u64 v[66:67], v[104:105], 0, s[8:9]
	v_mfma_f32_32x32x16_bf16 v[128:143], v[84:87], v[180:183], v[128:143]
	global_load_lds_dwordx4 v[66:67], off
	v_lshl_add_u64 v[104:105], v[104:105], 0, s[34:35]
	v_mfma_f32_32x32x16_bf16 v[184:199], v[84:87], v[236:239], v[184:199]
	s_add_i32 m0, s5, 0x8400
	v_lshl_add_u64 v[66:67], v[108:109], 0, s[8:9]
	v_mfma_f32_32x32x16_bf16 v[200:215], v[88:91], v[180:183], v[200:215]
	global_load_lds_dwordx4 v[66:67], off
	v_lshl_add_u64 v[108:109], v[108:109], 0, s[34:35]
	v_mfma_f32_32x32x16_bf16 v[216:231], v[88:91], v[236:239], v[216:231]
	s_add_i32 m0, s5, 0x8800
	v_lshl_add_u64 v[66:67], v[112:113], 0, s[8:9]
	v_mfma_f32_32x32x16_bf16 v[128:143], v[92:95], v[240:243], v[128:143]
	global_load_lds_dwordx4 v[66:67], off
	v_lshl_add_u64 v[112:113], v[112:113], 0, s[34:35]
	v_mfma_f32_32x32x16_bf16 v[184:199], v[92:95], v[244:247], v[184:199]
	s_add_i32 m0, s5, 0x8c00
	v_lshl_add_u64 v[66:67], v[116:117], 0, s[8:9]
	v_mfma_f32_32x32x16_bf16 v[200:215], v[96:99], v[240:243], v[200:215]
	global_load_lds_dwordx4 v[66:67], off
	v_lshl_add_u64 v[116:117], v[116:117], 0, s[34:35]
	v_mfma_f32_32x32x16_bf16 v[216:231], v[96:99], v[244:247], v[216:231]
	v_mfma_f32_32x32x16_bf16 v[128:143], v[100:103], v[248:251], v[128:143]
	v_mfma_f32_32x32x16_bf16 v[184:199], v[100:103], v[252:255], v[184:199]
	v_mfma_f32_32x32x16_bf16 v[200:215], v[144:147], v[248:251], v[200:215]
	v_mfma_f32_32x32x16_bf16 v[216:231], v[144:147], v[252:255], v[216:231]
	s_waitcnt vmcnt(4)
	s_barrier
	ds_read_b128 v[76:79], v68 offset:0
	ds_read_b128 v[80:83], v68 offset:4096
	ds_read_b128 v[148:151], v69 offset:32768
	ds_read_b128 v[152:155], v69 offset:36864
	ds_read_b128 v[84:87], v70 offset:0
	ds_read_b128 v[88:91], v70 offset:4096
	ds_read_b128 v[180:183], v71 offset:32768
	ds_read_b128 v[236:239], v71 offset:36864
	ds_read_b128 v[92:95], v72 offset:0
	ds_read_b128 v[96:99], v72 offset:4096
	ds_read_b128 v[240:243], v73 offset:32768
	ds_read_b128 v[244:247], v73 offset:36864
	ds_read_b128 v[100:103], v74 offset:0
	ds_read_b128 v[144:147], v74 offset:4096
	ds_read_b128 v[248:251], v75 offset:32768
	ds_read_b128 v[252:255], v75 offset:36864
	s_waitcnt lgkmcnt(12)
	v_mfma_f32_32x32x16_bf16 v[50:65], v[76:79], v[148:151], v[50:65]
	v_mfma_f32_32x32x16_bf16 v[34:49], v[76:79], v[152:155], v[34:49]
	v_mfma_f32_32x32x16_bf16 v[18:33], v[80:83], v[148:151], v[18:33]
	v_mfma_f32_32x32x16_bf16 v[2:17], v[80:83], v[152:155], v[2:17]
	s_waitcnt lgkmcnt(0)
	s_barrier
	v_mfma_f32_32x32x16_bf16 v[50:65], v[84:87], v[180:183], v[50:65]
	v_mfma_f32_32x32x16_bf16 v[34:49], v[84:87], v[236:239], v[34:49]
	v_mfma_f32_32x32x16_bf16 v[18:33], v[88:91], v[180:183], v[18:33]
	v_mfma_f32_32x32x16_bf16 v[2:17], v[88:91], v[236:239], v[2:17]
	v_mfma_f32_32x32x16_bf16 v[50:65], v[92:95], v[240:243], v[50:65]
	v_mfma_f32_32x32x16_bf16 v[34:49], v[92:95], v[244:247], v[34:49]
	v_mfma_f32_32x32x16_bf16 v[18:33], v[96:99], v[240:243], v[18:33]
	v_mfma_f32_32x32x16_bf16 v[2:17], v[96:99], v[244:247], v[2:17]
	v_mfma_f32_32x32x16_bf16 v[50:65], v[100:103], v[248:251], v[50:65]
	v_mfma_f32_32x32x16_bf16 v[34:49], v[100:103], v[252:255], v[34:49]
	v_mfma_f32_32x32x16_bf16 v[18:33], v[144:147], v[248:251], v[18:33]
	v_mfma_f32_32x32x16_bf16 v[2:17], v[144:147], v[252:255], v[2:17]
	s_waitcnt vmcnt(0)
	s_barrier
	ds_read_b128 v[76:79], v68 offset:32768
	ds_read_b128 v[80:83], v68 offset:36864
	ds_read_b128 v[84:87], v70 offset:32768
	ds_read_b128 v[88:91], v70 offset:36864
	ds_read_b128 v[92:95], v72 offset:32768
	ds_read_b128 v[96:99], v72 offset:36864
	ds_read_b128 v[100:103], v74 offset:32768
	ds_read_b128 v[144:147], v74 offset:36864
	s_waitcnt lgkmcnt(6)
	v_mfma_f32_32x32x16_bf16 v[128:143], v[76:79], v[148:151], v[128:143]
	v_mfma_f32_32x32x16_bf16 v[184:199], v[76:79], v[152:155], v[184:199]
	v_mfma_f32_32x32x16_bf16 v[200:215], v[80:83], v[148:151], v[200:215]
	v_mfma_f32_32x32x16_bf16 v[216:231], v[80:83], v[152:155], v[216:231]
	s_waitcnt lgkmcnt(0)
	s_barrier
	v_mfma_f32_32x32x16_bf16 v[128:143], v[84:87], v[180:183], v[128:143]
	v_mfma_f32_32x32x16_bf16 v[184:199], v[84:87], v[236:239], v[184:199]
	v_mfma_f32_32x32x16_bf16 v[200:215], v[88:91], v[180:183], v[200:215]
	v_mfma_f32_32x32x16_bf16 v[216:231], v[88:91], v[236:239], v[216:231]
	v_mfma_f32_32x32x16_bf16 v[128:143], v[92:95], v[240:243], v[128:143]
	v_mfma_f32_32x32x16_bf16 v[184:199], v[92:95], v[244:247], v[184:199]
	v_mfma_f32_32x32x16_bf16 v[200:215], v[96:99], v[240:243], v[200:215]
	v_mfma_f32_32x32x16_bf16 v[216:231], v[96:99], v[244:247], v[216:231]
	v_mfma_f32_32x32x16_bf16 v[128:143], v[100:103], v[248:251], v[128:143]
	v_mfma_f32_32x32x16_bf16 v[184:199], v[100:103], v[252:255], v[184:199]
	v_mfma_f32_32x32x16_bf16 v[200:215], v[144:147], v[248:251], v[200:215]
	v_mfma_f32_32x32x16_bf16 v[216:231], v[144:147], v[252:255], v[216:231]
	s_waitcnt vmcnt(0) lgkmcnt(0)
	s_barrier
	v_readlane_b32 s8, v232, 16
	v_readlane_b32 s9, v232, 17
	v_readlane_b32 s10, v234, 2
	v_readlane_b32 s11, v234, 3
	s_nop 3
	s_and_b64 s[8:9], s[8:9], exec
	s_cselect_b32 s9, s11, s79
	s_cselect_b32 s8, s10, s78
	v_and_b32_e32 v104, 15, v156
	v_lshlrev_b32_e32 v104, 4, v104
	v_bfe_u32 v105, v156, 4, 2
	v_lshrrev_b32_e32 v106, 6, v156
	v_lshlrev_b32_e32 v106, 14, v106
	v_or_b32_e32 v107, v106, v104
	v_lshrrev_b32_e32 v66, 1, v156
	v_and_b32_e32 v66, 0xffffffc0, v66
	v_lshlrev_b32_e32 v66, 10, v66
	v_and_b32_e32 v108, 64, v156
	v_or_b32_e32 v66, v66, v108
	v_mov_b32_e32 v67, 0
	v_lshlrev_b32_e32 v108, 12, v105
	v_add_u32_e32 v110, v104, v108
	v_mov_b32_e32 v111, 0
	v_lshl_add_u64 v[68:69], s[8:9], 0, v[110:111]
	v_and_b32_e32 v109, 31, v156
	v_lshlrev_b32_e32 v109, 2, v109
	v_bfe_u32 v112, v156, 5, 1
	v_lshlrev_b32_e32 v112, 10, v112
	v_or3_b32 v125, v106, v109, v112
	v_mov_b32_e32 v70, v108
	v_mov_b32_e32 v72, v104
	v_add_u32_e32 v74, 0x4000, v108
	v_add_u32_e32 v76, 0x8000, v108
	v_add_u32_e32 v78, 0xc000, v108
	v_add_u32_e32 v80, 0x10000, v108
	v_add_u32_e32 v82, 0x14000, v108
	v_add_u32_e32 v84, 0x18000, v108
	v_add_u32_e32 v86, 0x1c000, v108
	v_add_u32_e32 v88, 0x20000, v108
	v_add_u32_e32 v90, 0x24000, v108
	v_add_u32_e32 v92, 0x28000, v108
	v_add_u32_e32 v94, 0x2c000, v108
	v_add_u32_e32 v96, 0x30000, v108
	v_add_u32_e32 v98, 0x34000, v108
	v_add_u32_e32 v100, 0x38000, v108
	v_add_u32_e32 v102, 0x3c000, v108
	v_lshl_add_u32 v109, v105, 8, v107
	v_mov_b32_e32 v144, v109
	v_add_u32_e32 v145, 0x400, v109
	v_add_u32_e32 v146, 0x800, v109
	v_add_u32_e32 v147, 0xc00, v109
	v_add_u32_e32 v148, 0x1000, v109
	v_add_u32_e32 v149, 0x1400, v109
	v_add_u32_e32 v150, 0x1800, v109
	v_add_u32_e32 v151, 0x1c00, v109
	v_add_u32_e32 v152, 0x2000, v109
	v_add_u32_e32 v153, 0x2400, v109
	v_add_u32_e32 v154, 0x2800, v109
	v_add_u32_e32 v155, 0x2c00, v109
	v_add_u32_e32 v180, 0x3000, v109
	v_add_u32_e32 v181, 0x3400, v109
	v_add_u32_e32 v182, 0x3800, v109
	v_add_u32_e32 v183, 0x3c00, v109
	s_branch .LBB0_993
